# as before plus attention outputs stored write-through so the attention sub-barrier needs no L2 write-back; lnpass split at row group 1300
# baseline (speedup 1.0000x reference)
; #define LAS __attribute__((address_space(3)))
; __device__ __forceinline__ float fexp2(float x) { return __builtin_amdgcn_exp2f(x); }
; __device__ __forceinline__ void att_sample_unit(const Ctx& p, int bs, int h, LAS unsigned char* lds) {
;     ...
;     float l0 = A.l[0], l1 = A.l[1];
;     l0 += __shfl_xor(l0, 16); l0 += __shfl_xor(l0, 32); l1 += __shfl_xor(l1, 16); l1 += __shfl_xor(l1, 32);
;     LAS float* Ob = (LAS float*)lds; LAS float* ML = Ob + 8 * 2 * 8 * 4 * 64;
; #pragma unroll
;     for (int mm = 0; mm < 2; ++mm)
; #pragma unroll
;         for (int d = 0; d < 8; ++d)
; #pragma unroll
;             for (int r = 0; r < 4; ++r) Ob[((((wave * 2 + mm) * 8 + d) * 4 + r) << 6) + lane] = A.O[mm][d][r];
;     ML[(wave * 4 + 0) * 64 + lane] = A.m[0]; ML[(wave * 4 + 1) * 64 + lane] = A.m[1]; ML[(wave * 4 + 2) * 64 + lane] = l0; ML[(wave * 4 + 3) * 64 + lane] = l1;
;     __syncthreads();
;     {
;         float ms0 = -1e30f, ms1 = -1e30f;
; #pragma unroll
;         for (int w = 0; w < 8; ++w) { ms0 = fmaxf(ms0, ML[(w * 4 + 0) * 64 + lane]); ms1 = fmaxf(ms1, ML[(w * 4 + 1) * 64 + lane]); }
;         float L0 = 0.f, L1 = 0.f; f32x4 o0 = (f32x4){0.f, 0.f, 0.f, 0.f}, o1 = o0;
; #pragma unroll
;         for (int w = 0; w < 8; ++w) {
;             const float f0 = fexp2(ML[(w * 4 + 0) * 64 + lane] - ms0), f1 = fexp2(ML[(w * 4 + 1) * 64 + lane] - ms1);
.LBB0_1753:
	v_and_b32_e32 v2, 64, v143
	v_xor_b32_e32 v0, 16, v143
	v_add_u32_e32 v2, 64, v2
	v_cmp_lt_i32_e32 vcc, v0, v2
	v_xor_b32_e32 v3, 32, v143
	s_lshl_b32 s2, s68, 10
	v_cndmask_b32_e32 v0, v143, v0, vcc
	v_lshlrev_b32_e32 v68, 2, v0
	ds_bpermute_b32 v0, v68, v172
	ds_bpermute_b32 v60, v68, v171
	v_cmp_lt_i32_e32 vcc, v3, v2
	v_lshl_add_u32 v61, s68, 14, v161
	ds_write2st64_b32 v61, v40, v41 offset1:1
	ds_write2st64_b32 v61, v42, v43 offset0:2 offset1:3
	ds_write2st64_b32 v61, v52, v53 offset0:4 offset1:5
	ds_write2st64_b32 v61, v54, v55 offset0:6 offset1:7
	ds_write2st64_b32 v61, v4, v5 offset0:8 offset1:9
	ds_write2st64_b32 v61, v6, v7 offset0:10 offset1:11
	ds_write2st64_b32 v61, v36, v37 offset0:12 offset1:13
	ds_write2st64_b32 v61, v38, v39 offset0:14 offset1:15
	ds_write2st64_b32 v61, v12, v13 offset0:16 offset1:17
	ds_write2st64_b32 v61, v14, v15 offset0:18 offset1:19
	ds_write2st64_b32 v61, v28, v29 offset0:20 offset1:21
	ds_write2st64_b32 v61, v30, v31 offset0:22 offset1:23
	ds_write2st64_b32 v61, v16, v17 offset0:24 offset1:25
	ds_write2st64_b32 v61, v18, v19 offset0:26 offset1:27
	ds_write2st64_b32 v61, v76, v77 offset0:28 offset1:29
	ds_write2st64_b32 v61, v78, v79 offset0:30 offset1:31
	ds_write2st64_b32 v61, v48, v49 offset0:32 offset1:33
	ds_write2st64_b32 v61, v50, v51 offset0:34 offset1:35
	ds_write2st64_b32 v61, v56, v57 offset0:36 offset1:37
	ds_write2st64_b32 v61, v58, v59 offset0:38 offset1:39
	ds_write2st64_b32 v61, v8, v9 offset0:40 offset1:41
	ds_write2st64_b32 v61, v10, v11 offset0:42 offset1:43
	ds_write2st64_b32 v61, v44, v45 offset0:44 offset1:45
	ds_write2st64_b32 v61, v46, v47 offset0:46 offset1:47
	ds_write2st64_b32 v61, v20, v21 offset0:48 offset1:49
	ds_write2st64_b32 v61, v22, v23 offset0:50 offset1:51
	ds_write2st64_b32 v61, v32, v33 offset0:52 offset1:53
	ds_write2st64_b32 v61, v34, v35 offset0:54 offset1:55
	ds_write2st64_b32 v61, v24, v25 offset0:56 offset1:57
	ds_write2st64_b32 v61, v26, v27 offset0:58 offset1:59
	ds_write2st64_b32 v61, v80, v81 offset0:60 offset1:61
	ds_write2st64_b32 v61, v82, v83 offset0:62 offset1:63
	v_cndmask_b32_e32 v2, v143, v3, vcc
	s_waitcnt lgkmcnt(14)
	v_add_f32_e32 v0, v172, v0
	v_lshlrev_b32_e32 v69, 2, v2
	v_add_f32_e32 v3, v171, v60
	ds_bpermute_b32 v2, v69, v0
	ds_bpermute_b32 v60, v69, v3
	v_add_u32_e32 v88, s2, v161
	v_add_u32_e32 v67, 0x12300, v88
	v_add_u32_e32 v76, 0x16300, v88
	s_waitcnt lgkmcnt(1)
	v_add_f32_e32 v0, v0, v2
	s_waitcnt lgkmcnt(0)
	v_add_f32_e32 v2, v3, v60
	v_add_u32_e32 v3, s2, v162
	ds_write2st64_b32 v3, v169, v170 offset1:1
	ds_write2st64_b32 v3, v0, v2 offset0:2 offset1:3
	s_waitcnt lgkmcnt(0)
	s_barrier
	ds_read2st64_b32 v[4:5], v162 offset1:1
	ds_read2st64_b32 v[8:9], v162 offset0:4 offset1:5
	ds_read2st64_b32 v[18:19], v162 offset0:8 offset1:9
	ds_read2st64_b32 v[22:23], v162 offset0:12 offset1:13
	ds_read2st64_b32 v[20:21], v162 offset0:6 offset1:7
	ds_read2st64_b32 v[12:13], v162 offset0:2 offset1:3
	s_waitcnt lgkmcnt(4)
	v_max3_f32 v2, v5, s59, v9
	v_max3_f32 v0, v4, s59, v8
	ds_read2st64_b32 v[42:43], v162 offset0:14 offset1:15
	ds_read2st64_b32 v[30:31], v162 offset0:10 offset1:11
	s_waitcnt lgkmcnt(4)
	v_max3_f32 v6, v2, v19, v23
	ds_read2st64_b32 v[48:49], v162 offset0:16 offset1:17
	ds_read2st64_b32 v[52:53], v162 offset0:20 offset1:21
	ds_read2st64_b32 v[64:65], v162 offset0:24 offset1:25
	ds_read2st64_b32 v[2:3], v162 offset0:28 offset1:29
	ds_read2st64_b32 v[70:71], v162 offset0:22 offset1:23
	ds_read2st64_b32 v[58:59], v162 offset0:18 offset1:19
	v_max3_f32 v0, v0, v18, v22
	s_waitcnt lgkmcnt(4)
	v_max3_f32 v0, v0, v48, v52
	v_max3_f32 v6, v6, v49, v53
	s_waitcnt lgkmcnt(2)
	v_max3_f32 v86, v0, v64, v2
	v_max3_f32 v87, v6, v65, v3
	v_sub_f32_e32 v0, v4, v86
	v_exp_f32_e32 v6, v0
	v_sub_f32_e32 v0, v5, v87
	v_exp_f32_e32 v0, v0
	v_sub_f32_e32 v7, v8, v86
	v_exp_f32_e32 v7, v7
	v_sub_f32_e32 v8, v9, v87
	v_fma_f32 v36, v13, v0, 0
	v_mov_b32_e32 v13, v20
	v_pk_mul_f32 v[28:29], v[12:13], v[6:7]
	v_exp_f32_e32 v8, v8
	v_add_f32_e32 v9, 0, v28
	v_add_f32_e32 v44, v9, v29
	v_sub_f32_e32 v9, v19, v87
	v_exp_f32_e32 v9, v9
	v_sub_f32_e32 v18, v18, v86
	v_exp_f32_e32 v20, v18
	v_mov_b32_e32 v18, v21
	v_mov_b32_e32 v19, v31
	v_pk_mul_f32 v[40:41], v[8:9], v[18:19]
	v_mov_b32_e32 v31, v42
	v_add_f32_e32 v21, v36, v40
	v_add_f32_e32 v56, v21, v41
	v_sub_f32_e32 v21, v22, v86
	v_exp_f32_e32 v21, v21
	v_sub_f32_e32 v22, v23, v87
	v_exp_f32_e32 v22, v22
	v_sub_f32_e32 v42, v48, v86
	v_pk_mul_f32 v[54:55], v[20:21], v[30:31]
	v_mov_b32_e32 v48, v43
	v_add_f32_e32 v23, v44, v54
	v_add_f32_e32 v66, v23, v55
	v_sub_f32_e32 v23, v49, v87
	v_exp_f32_e32 v23, v23
	s_waitcnt lgkmcnt(0)
; __device__ __forceinline__ float fexp2(float x) { return __builtin_amdgcn_exp2f(x); }
; __device__ __forceinline__ float wave_sum(float v) { return wave_sum_fast(v); }
;     __device__ __forceinline__ const float* in(int i) const { return (const float*)ptr(i); }
; __device__ __forceinline__ float att_lambda(const Ctx& p, int lane) {
;     const float a = wave_sum(p.in(12)[lane] * p.in(13)[lane]), b = wave_sum(p.in(14)[lane] * p.in(15)[lane]);
;     return expf(a) - expf(b) + 0.2f;
; __device__ __forceinline__ void att_sample_unit(const Ctx& p, int bs, int h, LAS unsigned char* lds) {
;     ...
; #pragma unroll
;         for (int w = 0; w < 8; ++w) { ms0 = fmaxf(ms0, ML[(w * 4 + 0) * 64 + lane]); ms1 = fmaxf(ms1, ML[(w * 4 + 1) * 64 + lane]); }
;         float L0 = 0.f, L1 = 0.f; f32x4 o0 = (f32x4){0.f, 0.f, 0.f, 0.f}, o1 = o0;
; #pragma unroll
;         for (int w = 0; w < 8; ++w) {
;             const float f0 = fexp2(ML[(w * 4 + 0) * 64 + lane] - ms0), f1 = fexp2(ML[(w * 4 + 1) * 64 + lane] - ms1);
;             L0 += ML[(w * 4 + 2) * 64 + lane] * f0; L1 += ML[(w * 4 + 3) * 64 + lane] * f1;
; #pragma unroll
;             for (int r = 0; r < 4; ++r) { o0[r] += Ob[((((w * 2 + 0) * 8 + wave) * 4 + r) << 6) + lane] * f0; o1[r] += Ob[((((w * 2 + 1) * 8 + wave) * 4 + r) << 6) + lane] * f1; }
;         }
;         const float lam = att_lambda(p, lane);
	v_mov_b32_e32 v49, v59
	v_exp_f32_e32 v42, v42
	v_add_u32_e32 v54, 0x12100, v88
	v_pk_mul_f32 v[62:63], v[22:23], v[48:49]
	v_add_u32_e32 v48, 0x10000, v88
	v_add_f32_e32 v43, v56, v62
	v_add_f32_e32 v78, v43, v63
	v_sub_f32_e32 v43, v52, v86
	v_exp_f32_e32 v43, v43
	v_add_u32_e32 v56, 0x12000, v88
	v_add_u32_e32 v49, 0x10100, v88
	v_add_u32_e32 v55, 0x10200, v88
	v_add_u32_e32 v59, 0x12200, v88
	ds_read2st64_b32 v[32:33], v162 offset0:30 offset1:31
	ds_read2st64_b32 v[38:39], v162 offset0:26 offset1:27
	ds_read2st64_b32 v[26:27], v88 offset1:1
	ds_read2st64_b32 v[14:15], v88 offset0:32 offset1:33
	ds_read2st64_b32 v[4:5], v88 offset0:34 offset1:35
	ds_read2st64_b32 v[10:11], v88 offset0:2 offset1:3
	ds_read2st64_b32 v[34:35], v88 offset0:64 offset1:65
	ds_read2st64_b32 v[24:25], v88 offset0:96 offset1:97
	ds_read2st64_b32 v[12:13], v88 offset0:98 offset1:99
	ds_read2st64_b32 v[16:17], v88 offset0:66 offset1:67
	ds_read2st64_b32 v[46:47], v88 offset0:128 offset1:129
	ds_read2st64_b32 v[36:37], v88 offset0:160 offset1:161
	ds_read2st64_b32 v[18:19], v88 offset0:162 offset1:163
	ds_read2st64_b32 v[28:29], v88 offset0:130 offset1:131
	ds_read2st64_b32 v[50:51], v88 offset0:192 offset1:193
	ds_read2st64_b32 v[44:45], v88 offset0:224 offset1:225
	ds_read2st64_b32 v[30:31], v88 offset0:226 offset1:227
	ds_read2st64_b32 v[40:41], v88 offset0:194 offset1:195
	v_add_u32_e32 v62, 0x10300, v88
	ds_read_b32 v60, v48
	ds_read_b32 v61, v49
	ds_read_b32 v57, v54
	ds_read_b32 v54, v55
	ds_read_b32 v48, v59
	ds_read_b32 v55, v62
	ds_read_b32 v49, v67
	ds_read_b32 v56, v56
	v_mov_b32_e32 v59, v70
	v_pk_mul_f32 v[72:73], v[42:43], v[58:59]
	v_sub_f32_e32 v52, v53, v87
	v_add_f32_e32 v53, v66, v72
	v_add_f32_e32 v89, v53, v73
	v_sub_f32_e32 v53, v65, v87
	v_exp_f32_e32 v52, v52
	v_exp_f32_e32 v53, v53
	v_add_u32_e32 v66, 0x16000, v88
	v_add_u32_e32 v58, 0x14000, v88
	v_add_u32_e32 v59, 0x14100, v88
	v_add_u32_e32 v62, 0x16100, v88
	v_add_u32_e32 v63, 0x14200, v88
	v_add_u32_e32 v70, 0x16200, v88
	v_add_u32_e32 v72, 0x14300, v88
	ds_read_b32 v74, v58
	ds_read_b32 v75, v59
	ds_read_b32 v67, v62
	ds_read_b32 v62, v63
	ds_read_b32 v58, v70
	ds_read_b32 v63, v72
	ds_read_b32 v59, v76
	ds_read_b32 v66, v66
	v_mov_b32_e32 v70, v71
	s_waitcnt lgkmcnt(14)
	v_mov_b32_e32 v71, v39
	v_pk_mul_f32 v[76:77], v[52:53], v[70:71]
	v_mov_b32_e32 v70, s60
	ds_read_b128 v[70:73], v70
	v_lshlrev_b32_e32 v91, 2, v132
	v_add_u32_e32 v79, 0x18100, v88
	v_add_u32_e32 v80, 0x1a100, v88
	v_add_u32_e32 v82, 0x18200, v88
	s_waitcnt lgkmcnt(0)
	v_readfirstlane_b32 s2, v70
	v_readfirstlane_b32 s3, v71
	v_readfirstlane_b32 s4, v72
	v_readfirstlane_b32 s5, v73
	s_nop 2
	global_load_dword v92, v91, s[2:3]
	s_nop 0
	global_load_dword v93, v91, s[4:5]
	v_add_u32_e32 v83, 0x1a200, v88
	v_add_u32_e32 v85, 0x18300, v88
	v_mov_b32_e32 v70, s61
	v_add_f32_e32 v39, v78, v76
	v_add_u32_e32 v65, 0x1a000, v88
	v_add_u32_e32 v76, 0x18000, v88
	v_add_u32_e32 v90, 0x1a300, v88
	ds_read_b128 v[70:73], v70
	ds_read_b32 v78, v76
	ds_read_b32 v79, v79
	ds_read_b32 v81, v80
	ds_read_b32 v82, v82
	ds_read_b32 v84, v83
	ds_read_b32 v83, v85
	ds_read_b32 v85, v90
	ds_read_b32 v80, v65
	s_waitcnt lgkmcnt(8)
	v_readfirstlane_b32 s2, v70
	v_readfirstlane_b32 s3, v71
	v_readfirstlane_b32 s4, v72
	v_readfirstlane_b32 s5, v73
	s_nop 2
	global_load_dword v70, v91, s[2:3]
	s_nop 0
	global_load_dword v90, v91, s[4:5]
	v_sub_f32_e32 v64, v64, v86
	v_sub_f32_e32 v2, v2, v86
	v_exp_f32_e32 v64, v64
	v_exp_f32_e32 v65, v2
	v_sub_f32_e32 v2, v3, v87
	v_exp_f32_e32 v2, v2
	v_add_f32_e32 v71, v39, v77
	v_mov_b32_e32 v39, v32
	v_pk_mul_f32 v[38:39], v[64:65], v[38:39]
	v_mul_f32_e32 v119, v2, v33
	v_add_f32_e32 v89, v89, v38
	v_add_u32_e32 v32, 0x1c000, v88
	v_add_u32_e32 v33, 0x1c100, v88
	v_add_u32_e32 v38, 0x1e100, v88
	v_add_u32_e32 v72, 0x1c200, v88
	v_add_u32_e32 v77, 0x1e200, v88
	v_add_u32_e32 v87, 0x1c300, v88
	v_add_u32_e32 v3, 0x1e000, v88
	v_add_u32_e32 v88, 0x1e300, v88
	ds_read_b32 v32, v32
	ds_read_b32 v33, v33
	ds_read_b32 v73, v38
	ds_read_b32 v76, v72
	ds_read_b32 v86, v77
	ds_read_b32 v77, v87
	ds_read_b32 v87, v88
	ds_read_b32 v72, v3
	v_pk_fma_f32 v[26:27], v[6:7], v[26:27], 0 op_sel_hi:[0,1,0]
	v_mov_b32_e32 v38, v7
	v_pk_fma_f32 v[26:27], v[38:39], v[34:35], v[26:27] op_sel_hi:[0,1,1]
	v_pk_fma_f32 v[26:27], v[20:21], v[46:47], v[26:27] op_sel_hi:[0,1,1]
	v_mov_b32_e32 v34, v21
	v_pk_fma_f32 v[26:27], v[34:35], v[50:51], v[26:27] op_sel_hi:[0,1,1]
	v_pk_fma_f32 v[26:27], v[42:43], v[60:61], v[26:27] op_sel_hi:[0,1,1]
	v_mov_b32_e32 v46, v43
	v_pk_fma_f32 v[14:15], v[0:1], v[14:15], 0 op_sel_hi:[0,1,0]
	v_pk_fma_f32 v[4:5], v[0:1], v[4:5], 0 op_sel_hi:[0,1,0]
	v_pk_fma_f32 v[26:27], v[46:47], v[74:75], v[26:27] op_sel_hi:[0,1,1]
	v_pk_fma_f32 v[14:15], v[8:9], v[24:25], v[14:15] op_sel_hi:[0,1,1]
	v_mov_b32_e32 v24, v9
	v_pk_fma_f32 v[4:5], v[8:9], v[12:13], v[4:5] op_sel_hi:[0,1,1]
	s_waitcnt lgkmcnt(14)
	v_pk_fma_f32 v[26:27], v[64:65], v[78:79], v[26:27] op_sel_hi:[0,1,1]
	v_mov_b32_e32 v50, v65
	v_pk_fma_f32 v[14:15], v[24:25], v[36:37], v[14:15] op_sel_hi:[0,1,1]
	v_pk_fma_f32 v[4:5], v[24:25], v[18:19], v[4:5] op_sel_hi:[0,1,1]
	s_waitcnt lgkmcnt(6)
	v_pk_fma_f32 v[26:27], v[50:51], v[32:33], v[26:27] op_sel_hi:[0,1,1]
	v_pk_fma_f32 v[14:15], v[22:23], v[44:45], v[14:15] op_sel_hi:[0,1,1]
	v_mov_b32_e32 v32, v23
	v_pk_fma_f32 v[4:5], v[22:23], v[30:31], v[4:5] op_sel_hi:[0,1,1]
	v_pk_fma_f32 v[14:15], v[32:33], v[56:57], v[14:15] op_sel_hi:[0,1,1]
	v_pk_fma_f32 v[4:5], v[32:33], v[48:49], v[4:5] op_sel_hi:[0,1,1]
	v_pk_fma_f32 v[14:15], v[52:53], v[66:67], v[14:15] op_sel_hi:[0,1,1]
	v_mov_b32_e32 v36, v53
	v_pk_fma_f32 v[4:5], v[52:53], v[58:59], v[4:5] op_sel_hi:[0,1,1]
	v_pk_fma_f32 v[14:15], v[36:37], v[80:81], v[14:15] op_sel_hi:[0,1,1]
	v_pk_fma_f32 v[4:5], v[36:37], v[84:85], v[4:5] op_sel_hi:[0,1,1]
	s_waitcnt lgkmcnt(0)
; #define LAS __attribute__((address_space(3)))
; __device__ __forceinline__ unsigned pk2(float lo, float hi) { f32x2 v = {lo, hi}; bf16x2_t b = __builtin_convertvector(v, bf16x2_t); return __builtin_bit_cast(unsigned, b); }
; __device__ __forceinline__ float wave_sum(float v) { return wave_sum_fast(v); }
;     __device__ __forceinline__ const float* in(int i) const { return (const float*)ptr(i); }
; __device__ __forceinline__ float att_lambda(const Ctx& p, int lane) {
;     const float a = wave_sum(p.in(12)[lane] * p.in(13)[lane]), b = wave_sum(p.in(14)[lane] * p.in(15)[lane]);
;     return expf(a) - expf(b) + 0.2f;
; }
; __device__ __forceinline__ void att_sample_unit(const Ctx& p, int bs, int h, LAS unsigned char* lds) {
;     ...
;         const float lam = att_lambda(p, lane);
;         const f32x4 o = o0 * (1.f / L0) - o1 * (lam / L1);
;         float ss = (o[0] * o[0] + o[1] * o[1]) + (o[2] * o[2] + o[3] * o[3]);
;         ss += __shfl_xor(ss, 16); ss += __shfl_xor(ss, 32);
;         LAS float* SS = ML + 8 * 4 * 64;
;         SS[wave * 64 + lane] = ss;
;         __syncthreads();
;         float tot = 0.f;
; #pragma unroll
;         for (int w = 0; w < 8; ++w) tot += SS[w * 64 + lane];
;         const float rs = 0.8f / sqrtf(tot * (1.f / 128.f) + EPS);
;         const f32x4 gg = *(const f32x4*)(p.in(16) + 16 * wave + 4 * g);
;         u32x2 wv; wv.x = pk2(o[0] * rs * gg[0], o[1] * rs * gg[1]); wv.y = pk2(o[2] * rs * gg[2], o[3] * rs * gg[3]);
;         *(u32x2*)(qrow + 16 * wave + 4 * g) = wv;
	v_pk_fma_f32 v[14:15], v[2:3], v[72:73], v[14:15] op_sel_hi:[0,1,1]
	v_pk_fma_f32 v[2:3], v[2:3], v[86:87], v[4:5] op_sel_hi:[0,1,1]
	v_pk_fma_f32 v[6:7], v[6:7], v[10:11], 0 op_sel_hi:[0,1,0]
	v_add_f32_e32 v0, v89, v39
	v_pk_fma_f32 v[6:7], v[38:39], v[16:17], v[6:7] op_sel_hi:[0,1,1]
	v_pk_fma_f32 v[6:7], v[20:21], v[28:29], v[6:7] op_sel_hi:[0,1,1]
	v_pk_fma_f32 v[6:7], v[34:35], v[40:41], v[6:7] op_sel_hi:[0,1,1]
	v_pk_fma_f32 v[6:7], v[42:43], v[54:55], v[6:7] op_sel_hi:[0,1,1]
	v_pk_fma_f32 v[6:7], v[46:47], v[62:63], v[6:7] op_sel_hi:[0,1,1]
	v_pk_fma_f32 v[6:7], v[64:65], v[82:83], v[6:7] op_sel_hi:[0,1,1]
	v_pk_fma_f32 v[6:7], v[50:51], v[76:77], v[6:7] op_sel_hi:[0,1,1]
	s_lshl_b32 s4, s68, 6
	s_waitcnt vmcnt(2)
	v_mul_f32_e32 v4, v92, v93
	s_nop 1
	v_mov_b32_dpp v4, v4 quad_perm:[1,0,3,2] row_mask:0xf bank_mask:0xf bound_ctrl:1
	v_fmac_f32_e32 v4, v92, v93
	s_nop 1
	v_add_f32_dpp v4, v4, v4 quad_perm:[2,3,0,1] row_mask:0xf bank_mask:0xf bound_ctrl:1
	s_nop 1
	v_add_f32_dpp v4, v4, v4 row_half_mirror row_mask:0xf bank_mask:0xf bound_ctrl:1
	s_nop 1
	v_add_f32_dpp v4, v4, v4 row_mirror row_mask:0xf bank_mask:0xf bound_ctrl:1
	v_mov_b32_e32 v5, v4
	s_nop 1
	v_permlane16_swap_b32_e32 v4, v5
	v_add_f32_e32 v4, v4, v5
	v_mov_b32_e32 v5, v4
	s_nop 1
	v_permlane32_swap_b32_e32 v4, v5
	v_add_f32_e32 v4, v4, v5
	s_waitcnt vmcnt(0)
	v_mul_f32_e32 v5, v70, v90
	v_mul_f32_e32 v9, 0x3fb8aa3b, v4
	v_fma_f32 v10, v4, s62, -v9
	v_mov_b32_dpp v5, v5 quad_perm:[1,0,3,2] row_mask:0xf bank_mask:0xf bound_ctrl:1
	v_fmac_f32_e32 v5, v70, v90
	v_rndne_f32_e32 v11, v9
	v_fmac_f32_e32 v10, 0x32a5705f, v4
	v_add_f32_dpp v5, v5, v5 quad_perm:[2,3,0,1] row_mask:0xf bank_mask:0xf bound_ctrl:1
	v_sub_f32_e32 v9, v9, v11
	v_add_f32_e32 v9, v9, v10
	v_add_f32_dpp v5, v5, v5 row_half_mirror row_mask:0xf bank_mask:0xf bound_ctrl:1
	v_exp_f32_e32 v9, v9
	v_cvt_i32_f32_e32 v10, v11
	v_add_f32_dpp v5, v5, v5 row_mirror row_mask:0xf bank_mask:0xf bound_ctrl:1
	v_mov_b32_e32 v8, v5
	s_nop 1
	v_permlane16_swap_b32_e32 v5, v8
	v_add_f32_e32 v5, v5, v8
	v_mov_b32_e32 v8, v5
	s_nop 1
	v_permlane32_swap_b32_e32 v5, v8
	v_add_f32_e32 v5, v5, v8
	v_ldexp_f32 v8, v9, v10
	v_mul_f32_e32 v9, 0x3fb8aa3b, v5
	v_fma_f32 v10, v5, s62, -v9
	v_rndne_f32_e32 v11, v9
	v_fmac_f32_e32 v10, 0x32a5705f, v5
	v_sub_f32_e32 v9, v9, v11
	v_add_f32_e32 v9, v9, v10
	v_exp_f32_e32 v9, v9
	v_cvt_i32_f32_e32 v10, v11
	v_cmp_ngt_f32_e32 vcc, s63, v4
	s_nop 1
	v_cndmask_b32_e32 v8, 0, v8, vcc
	v_cmp_nlt_f32_e32 vcc, s64, v4
	s_nop 1
	v_cndmask_b32_e32 v4, v168, v8, vcc
	v_ldexp_f32 v8, v9, v10
	v_div_scale_f32 v9, s[2:3], v0, v0, 1.0
	v_rcp_f32_e32 v10, v9
	v_cmp_ngt_f32_e32 vcc, s63, v5
	s_nop 1
	v_cndmask_b32_e32 v8, 0, v8, vcc
	v_cmp_nlt_f32_e32 vcc, s64, v5
	s_nop 1
	v_cndmask_b32_e32 v5, v168, v8, vcc
	v_fma_f32 v8, -v9, v10, 1.0
	v_fmac_f32_e32 v10, v8, v10
	v_div_scale_f32 v8, vcc, 1.0, v0, 1.0
	v_mul_f32_e32 v11, v8, v10
	v_sub_f32_e32 v70, v4, v5
	v_fma_f32 v12, -v9, v11, v8
	v_pk_add_f32 v[4:5], v[70:71], v[118:119]
	v_fmac_f32_e32 v11, v12, v10
	v_fma_f32 v8, -v9, v11, v8
	v_div_scale_f32 v9, s[2:3], v5, v5, v4
	v_rcp_f32_e32 v12, v9
	v_div_fmas_f32 v8, v8, v10, v11
	v_div_fixup_f32 v0, v8, v0, 1.0
	s_and_b32 s2, s69, 0x3fffffc0
	v_fma_f32 v8, -v9, v12, 1.0
	v_fmac_f32_e32 v12, v8, v12
	v_div_scale_f32 v8, vcc, v4, v5, v4
	v_mul_f32_e32 v10, v8, v12
	v_fma_f32 v11, -v9, v10, v8
	v_fmac_f32_e32 v10, v11, v12
	v_fma_f32 v8, -v9, v10, v8
	v_div_fmas_f32 v8, v8, v12, v10
	v_div_fixup_f32 v4, v8, v5, v4
	v_pk_mul_f32 v[8:9], v[14:15], v[4:5] op_sel_hi:[1,0]
	v_pk_mul_f32 v[2:3], v[2:3], v[4:5] op_sel_hi:[1,0]
	v_pk_fma_f32 v[8:9], v[0:1], v[26:27], v[8:9] op_sel_hi:[0,1,1] neg_lo:[0,0,1] neg_hi:[0,0,1]
	v_pk_fma_f32 v[6:7], v[0:1], v[6:7], v[2:3] op_sel_hi:[0,1,1] neg_lo:[0,0,1] neg_hi:[0,0,1]
	v_mul_f32_e32 v0, v9, v9
	v_mul_f32_e32 v2, v7, v7
	v_fmac_f32_e32 v0, v8, v8
	v_fmac_f32_e32 v2, v6, v6
	v_add_f32_e32 v0, v0, v2
	ds_bpermute_b32 v2, v68, v0
	s_waitcnt lgkmcnt(0)
	v_add_f32_e32 v0, v0, v2
	ds_bpermute_b32 v2, v69, v0
	s_waitcnt lgkmcnt(0)
	v_add_f32_e32 v0, v0, v2
	v_lshl_add_u32 v2, s2, 2, v163
	ds_write_b32 v2, v0
	v_mov_b32_e32 v0, s67
	s_waitcnt lgkmcnt(0)
	s_barrier
	ds_read_b64 v[2:3], v0
	v_lshlrev_b32_e32 v0, 2, v134
	s_waitcnt lgkmcnt(0)
	v_readfirstlane_b32 s2, v2
	v_readfirstlane_b32 s3, v3
	s_add_u32 s2, s2, s4
	s_addc_u32 s3, s3, 0
	s_lshl_b32 s42, s68, 5
	s_nop 1
	global_load_dwordx4 v[2:5], v0, s[2:3]
	ds_read2st64_b32 v[10:11], v163 offset1:1
	ds_read2st64_b32 v[12:13], v163 offset0:2 offset1:3
	ds_read2st64_b32 v[14:15], v163 offset0:4 offset1:5
	ds_read2st64_b32 v[16:17], v163 offset0:6 offset1:7
	s_waitcnt lgkmcnt(3)
	v_add_f32_e32 v0, 0, v10
	v_add_f32_e32 v0, v0, v11
	s_waitcnt lgkmcnt(2)
	v_add_f32_e32 v0, v0, v12
	v_add_f32_e32 v0, v0, v13
	s_waitcnt lgkmcnt(1)
	v_add_f32_e32 v0, v0, v14
	v_add_f32_e32 v0, v0, v15
	s_waitcnt lgkmcnt(0)
	v_add_f32_e32 v0, v0, v16
	v_add_f32_e32 v0, v0, v17
	v_fmamk_f32 v0, v0, 0x3c000000, v165
	v_mul_f32_e32 v10, 0x4f800000, v0
	v_cmp_gt_f32_e32 vcc, s65, v0
	s_nop 1
	v_cndmask_b32_e32 v0, v0, v10, vcc
	v_sqrt_f32_e32 v10, v0
	s_nop 0
	v_add_u32_e32 v11, -1, v10
	v_fma_f32 v12, -v11, v10, v0
	v_cmp_ge_f32_e64 s[2:3], 0, v12
	v_add_u32_e32 v12, 1, v10
	s_nop 0
	v_cndmask_b32_e64 v11, v10, v11, s[2:3]
	v_fma_f32 v10, -v12, v10, v0
	v_cmp_lt_f32_e64 s[2:3], 0, v10
	s_nop 1
	v_cndmask_b32_e64 v10, v11, v12, s[2:3]
	v_mul_f32_e32 v11, 0x37800000, v10
	v_cndmask_b32_e32 v10, v10, v11, vcc
	v_cmp_class_f32_e32 vcc, v0, v166
	s_nop 1
	v_cndmask_b32_e32 v0, v10, v0, vcc
	v_div_scale_f32 v10, s[2:3], v0, v0, s66
	v_rcp_f32_e32 v11, v10
	s_mov_b64 s[2:3], 0
	v_fma_f32 v12, -v10, v11, 1.0
	v_fmac_f32_e32 v11, v12, v11
	v_div_scale_f32 v12, vcc, s66, v0, s66
	v_mul_f32_e32 v13, v12, v11
	v_fma_f32 v14, -v10, v13, v12
	v_fmac_f32_e32 v13, v14, v11
	v_fma_f32 v10, -v10, v13, v12
	v_div_fmas_f32 v10, v10, v11, v13
	v_div_fixup_f32 v0, v10, v0, s66
	v_pk_mul_f32 v[8:9], v[8:9], v[0:1] op_sel_hi:[1,0]
	v_pk_mul_f32 v[6:7], v[6:7], v[0:1] op_sel_hi:[1,0]
	v_lshlrev_b32_e32 v0, 1, v134
	s_waitcnt vmcnt(0)
	v_pk_mul_f32 v[2:3], v[8:9], v[2:3]
	v_pk_mul_f32 v[4:5], v[6:7], v[4:5]
	v_cvt_pk_bf16_f32 v2, v2, v3
	v_cvt_pk_bf16_f32 v3, v4, v5
	v_lshl_add_u64 v[4:5], v[120:121], 0, s[42:43]
	v_lshl_add_u64 v[4:5], v[4:5], 0, v[0:1]
	global_store_dwordx2 v[4:5], v[2:3], off sc1
	s_barrier

; __device__ __forceinline__ unsigned pk2(float lo, float hi) { f32x2 v = {lo, hi}; bf16x2_t b = __builtin_convertvector(v, bf16x2_t); return __builtin_bit_cast(unsigned, b); }
; __device__ __forceinline__ float wave_sum(float v) { return wave_sum_fast(v); }
;     __device__ __forceinline__ const float* in(int i) const { return (const float*)ptr(i); }
; __device__ __forceinline__ void att_final(const AttAcc& A, float l0, float l1, float lam, const float* subg, bf16_t* orow, int g) {
;     const float i0 = 1.f / l0, i1 = lam / l1;
;     f32x4 o[8]; float ss = 0.f;
; #pragma unroll
;     for (int d = 0; d < 8; ++d) { o[d] = A.O[0][d] * i0 - A.O[1][d] * i1; ss += (o[d][0] * o[d][0] + o[d][1] * o[d][1]) + (o[d][2] * o[d][2] + o[d][3] * o[d][3]); }
;     ss += __shfl_xor(ss, 16); ss += __shfl_xor(ss, 32);
;     const float rs = 0.8f / sqrtf(ss * (1.f / 128.f) + EPS);
; #pragma unroll
;     for (int d = 0; d < 8; ++d) { const f32x4 gg = *(const f32x4*)(subg + 16 * d + 4 * g);
;         u32x2 w; w.x = pk2(o[d][0] * rs * gg[0], o[d][1] * rs * gg[1]); w.y = pk2(o[d][2] * rs * gg[2], o[d][3] * rs * gg[3]);
;         *(u32x2*)(orow + 16 * d + 4 * g) = w; }
; }
; __device__ __forceinline__ float att_lambda(const Ctx& p, int lane) {
;     const float a = wave_sum(p.in(12)[lane] * p.in(13)[lane]), b = wave_sum(p.in(14)[lane] * p.in(15)[lane]);
;     return expf(a) - expf(b) + 0.2f;
; }
; __device__ __forceinline__ void att_prompt_unit(const Ctx& p, int bh, int qb, LAS unsigned char* lds) {
;     ...
;     float l0 = A.l[0], l1 = A.l[1];
;     l0 += __shfl_xor(l0, 16); l0 += __shfl_xor(l0, 32); l1 += __shfl_xor(l1, 16); l1 += __shfl_xor(l1, 32);
;     const float lam = att_lambda(p, lane);
;     att_final(A, l0, l1, lam, p.in(16), qrow, g);
.LBB0_1782:
	v_mov_b32_e32 v0, s24
	s_barrier
	ds_read_b128 v[68:71], v0
	v_mov_b32_e32 v2, s25
	ds_read_b128 v[72:75], v2
	v_lshlrev_b32_e32 v0, 2, v132
	v_mov_b32_e32 v2, s34
	s_waitcnt lgkmcnt(1)
	v_readfirstlane_b32 s2, v68
	v_readfirstlane_b32 s3, v69
	v_readfirstlane_b32 s14, v70
	v_readfirstlane_b32 s15, v71
	ds_read_b64 v[2:3], v2
	s_waitcnt lgkmcnt(1)
	v_readfirstlane_b32 s16, v72
	v_readfirstlane_b32 s17, v73
	v_readfirstlane_b32 s44, v74
	v_readfirstlane_b32 s45, v75
	global_load_dword v68, v0, s[2:3]
	global_load_dword v69, v0, s[14:15]
	s_nop 0
	global_load_dword v70, v0, s[16:17]
	s_nop 0
	global_load_dword v71, v0, s[44:45]
	v_and_b32_e32 v72, 64, v143
	v_xor_b32_e32 v0, 16, v143
	v_add_u32_e32 v72, 64, v72
	v_cmp_lt_i32_e32 vcc, v0, v72
	v_xor_b32_e32 v73, 32, v143
	s_waitcnt lgkmcnt(0)
	v_readfirstlane_b32 s14, v2
	v_cndmask_b32_e32 v0, v143, v0, vcc
	v_lshlrev_b32_e32 v74, 2, v0
	ds_bpermute_b32 v0, v74, v137
	v_cmp_lt_i32_e32 vcc, v73, v72
	v_readfirstlane_b32 s15, v3
	s_waitcnt lgkmcnt(0)
	v_add_f32_e32 v0, v137, v0
	v_cndmask_b32_e32 v72, v143, v73, vcc
	v_lshlrev_b32_e32 v72, 2, v72
	ds_bpermute_b32 v75, v72, v0
	ds_bpermute_b32 v73, v74, v139
	s_waitcnt lgkmcnt(1)
	v_add_f32_e32 v0, v0, v75
	v_div_scale_f32 v2, s[2:3], v0, v0, 1.0
	s_waitcnt lgkmcnt(0)
	v_add_f32_e32 v3, v139, v73
	v_rcp_f32_e32 v73, v2
	v_div_scale_f32 v75, vcc, 1.0, v0, 1.0
	ds_bpermute_b32 v149, v72, v3
	v_fma_f32 v76, -v2, v73, 1.0
	v_fmac_f32_e32 v73, v76, v73
	v_mul_f32_e32 v76, v75, v73
	v_fma_f32 v77, -v2, v76, v75
	v_fmac_f32_e32 v76, v77, v73
	v_fma_f32 v2, -v2, v76, v75
	v_div_fmas_f32 v73, v2, v73, v76
	v_div_fixup_f32 v0, v73, v0, 1.0
	s_waitcnt vmcnt(2)
	v_mul_f32_e32 v75, v68, v69
	s_nop 1
	v_mov_b32_dpp v75, v75 quad_perm:[1,0,3,2] row_mask:0xf bank_mask:0xf bound_ctrl:1
	s_waitcnt vmcnt(0)
	v_mul_f32_e32 v77, v70, v71
	v_fmac_f32_e32 v75, v68, v69
	s_nop 0
	v_mov_b32_dpp v77, v77 quad_perm:[1,0,3,2] row_mask:0xf bank_mask:0xf bound_ctrl:1
	v_fmac_f32_e32 v77, v70, v71
	v_add_f32_dpp v68, v75, v75 quad_perm:[2,3,0,1] row_mask:0xf bank_mask:0xf bound_ctrl:1
	s_nop 0
	v_add_f32_dpp v69, v77, v77 quad_perm:[2,3,0,1] row_mask:0xf bank_mask:0xf bound_ctrl:1
	v_add_f32_dpp v68, v68, v68 row_half_mirror row_mask:0xf bank_mask:0xf bound_ctrl:1
	s_nop 0
	v_add_f32_dpp v69, v69, v69 row_half_mirror row_mask:0xf bank_mask:0xf bound_ctrl:1
	v_add_f32_dpp v68, v68, v68 row_mirror row_mask:0xf bank_mask:0xf bound_ctrl:1
	v_mov_b32_e32 v70, v68
	v_add_f32_dpp v69, v69, v69 row_mirror row_mask:0xf bank_mask:0xf bound_ctrl:1
	v_mov_b32_e32 v71, v69
	v_permlane16_swap_b32_e32 v68, v70
	s_nop 0
	v_permlane16_swap_b32_e32 v69, v71
	v_add_f32_e32 v68, v68, v70
	v_add_f32_e32 v69, v69, v71
	v_mov_b32_e32 v70, v68
	v_mov_b32_e32 v71, v69
	s_nop 0
	v_permlane32_swap_b32_e32 v68, v70
	v_permlane32_swap_b32_e32 v69, v71
	v_add_f32_e32 v68, v68, v70
	v_add_f32_e32 v69, v69, v71
	v_mul_f32_e32 v70, 0x3fb8aa3b, v68
	v_mul_f32_e32 v71, 0x3fb8aa3b, v69
	v_fma_f32 v75, v68, s26, -v70
	v_rndne_f32_e32 v77, v70
	v_fma_f32 v78, v69, s26, -v71
	v_rndne_f32_e32 v79, v71
	v_fmac_f32_e32 v75, 0x32a5705f, v68
	v_sub_f32_e32 v70, v70, v77
	v_fmac_f32_e32 v78, 0x32a5705f, v69
	v_sub_f32_e32 v71, v71, v79
	v_add_f32_e32 v70, v70, v75
	v_cvt_i32_f32_e32 v77, v77
	v_add_f32_e32 v71, v71, v78
	v_exp_f32_e32 v70, v70
	v_cvt_i32_f32_e32 v79, v79
	v_exp_f32_e32 v71, v71
	v_cmp_ngt_f32_e32 vcc, s27, v68
	v_ldexp_f32 v2, v70, v77
	v_ldexp_f32 v70, v71, v79
	v_cndmask_b32_e32 v2, 0, v2, vcc
	v_cmp_ngt_f32_e32 vcc, s27, v69
	s_nop 1
	v_cndmask_b32_e32 v70, 0, v70, vcc
	v_cmp_nlt_f32_e32 vcc, s33, v68
	s_nop 1
	v_cndmask_b32_e32 v2, v168, v2, vcc
	v_cmp_nlt_f32_e32 vcc, s33, v69
	s_nop 1
	v_cndmask_b32_e32 v68, v168, v70, vcc
	v_sub_f32_e32 v2, v2, v68
	s_waitcnt lgkmcnt(0)
	v_pk_add_f32 v[2:3], v[2:3], v[148:149]
	s_nop 0
	v_div_scale_f32 v68, s[2:3], v3, v3, v2
	v_rcp_f32_e32 v69, v68
	v_div_scale_f32 v70, vcc, v2, v3, v2
	v_fma_f32 v71, -v68, v69, 1.0
	v_fmac_f32_e32 v69, v71, v69
	v_mul_f32_e32 v71, v70, v69
	v_fma_f32 v73, -v68, v71, v70
	v_fmac_f32_e32 v71, v73, v69
	v_fma_f32 v68, -v68, v71, v70
	v_div_fmas_f32 v68, v68, v69, v71
	v_div_fixup_f32 v2, v68, v3, v2
	v_pk_mul_f32 v[60:61], v[60:61], v[2:3] op_sel_hi:[1,0]
	v_pk_mul_f32 v[52:53], v[52:53], v[2:3] op_sel_hi:[1,0]
	v_pk_mul_f32 v[62:63], v[62:63], v[2:3] op_sel_hi:[1,0]
	v_pk_fma_f32 v[60:61], v[64:65], v[0:1], v[60:61] op_sel_hi:[1,0,1] neg_lo:[0,0,1] neg_hi:[0,0,1]
	v_pk_mul_f32 v[54:55], v[54:55], v[2:3] op_sel_hi:[1,0]
	v_pk_fma_f32 v[52:53], v[56:57], v[0:1], v[52:53] op_sel_hi:[1,0,1] neg_lo:[0,0,1] neg_hi:[0,0,1]
	v_pk_fma_f32 v[62:63], v[66:67], v[0:1], v[62:63] op_sel_hi:[1,0,1] neg_lo:[0,0,1] neg_hi:[0,0,1]
	v_pk_fma_f32 v[54:55], v[58:59], v[0:1], v[54:55] op_sel_hi:[1,0,1] neg_lo:[0,0,1] neg_hi:[0,0,1]
	v_mov_b32_e32 v58, v61
	v_mov_b32_e32 v59, v53
	v_mov_b32_e32 v56, v60
	v_mov_b32_e32 v57, v52
	v_pk_mul_f32 v[58:59], v[58:59], v[58:59]
	v_mov_b32_e32 v64, v63
	v_mov_b32_e32 v65, v55
	v_pk_mul_f32 v[46:47], v[46:47], v[2:3] op_sel_hi:[1,0]
	v_pk_mul_f32 v[44:45], v[44:45], v[2:3] op_sel_hi:[1,0]
	v_pk_mul_f32 v[36:37], v[36:37], v[2:3] op_sel_hi:[1,0]
	v_pk_fma_f32 v[56:57], v[56:57], v[56:57], v[58:59]
	v_mov_b32_e32 v58, v62
	v_mov_b32_e32 v59, v54
	v_pk_mul_f32 v[64:65], v[64:65], v[64:65]
	v_pk_fma_f32 v[44:45], v[48:49], v[0:1], v[44:45] op_sel_hi:[1,0,1] neg_lo:[0,0,1] neg_hi:[0,0,1]
	v_pk_fma_f32 v[46:47], v[50:51], v[0:1], v[46:47] op_sel_hi:[1,0,1] neg_lo:[0,0,1] neg_hi:[0,0,1]
	v_pk_fma_f32 v[36:37], v[40:41], v[0:1], v[36:37] op_sel_hi:[1,0,1] neg_lo:[0,0,1] neg_hi:[0,0,1]
; __device__ __forceinline__ void att_final(const AttAcc& A, float l0, float l1, float lam, const float* subg, bf16_t* orow, int g) {
;     const float i0 = 1.f / l0, i1 = lam / l1;
;     f32x4 o[8]; float ss = 0.f;
; #pragma unroll
;     for (int d = 0; d < 8; ++d) { o[d] = A.O[0][d] * i0 - A.O[1][d] * i1; ss += (o[d][0] * o[d][0] + o[d][1] * o[d][1]) + (o[d][2] * o[d][2] + o[d][3] * o[d][3]); }
;     ss += __shfl_xor(ss, 16); ss += __shfl_xor(ss, 32);
;     const float rs = 0.8f / sqrtf(ss * (1.f / 128.f) + EPS);
; #pragma unroll
;     for (int d = 0; d < 8; ++d) { const f32x4 gg = *(const f32x4*)(subg + 16 * d + 4 * g);
	v_pk_fma_f32 v[58:59], v[58:59], v[58:59], v[64:65]
	v_pk_mul_f32 v[48:49], v[46:47], v[46:47]
	v_pk_mul_f32 v[50:51], v[44:45], v[44:45]
	v_pk_mul_f32 v[38:39], v[38:39], v[2:3] op_sel_hi:[1,0]
	v_mul_f32_e32 v40, v36, v36
	v_pk_add_f32 v[56:57], v[56:57], v[58:59]
	v_pk_mov_b32 v[58:59], v[50:51], v[48:49] op_sel:[1,0]
	v_mov_b32_e32 v51, v49
	v_pk_fma_f32 v[38:39], v[42:43], v[0:1], v[38:39] op_sel_hi:[1,0,1] neg_lo:[0,0,1] neg_hi:[0,0,1]
	v_pk_fma_f32 v[40:41], v[36:37], v[36:37], v[40:41] op_sel_hi:[1,1,0]
	v_pk_add_f32 v[48:49], v[58:59], v[50:51]
	v_mul_f32_e32 v40, v38, v38
	v_pk_mul_f32 v[32:33], v[32:33], v[2:3] op_sel_hi:[1,0]
	v_pk_mul_f32 v[34:35], v[34:35], v[2:3] op_sel_hi:[1,0]
	v_pk_add_f32 v[56:57], v[56:57], v[56:57] op_sel_hi:[0,1]
	v_pk_add_f32 v[48:49], v[48:49], v[48:49] op_sel_hi:[0,1]
	v_pk_fma_f32 v[42:43], v[38:39], v[38:39], v[40:41] op_sel_hi:[1,1,0]
	v_pk_fma_f32 v[30:31], v[30:31], v[0:1], v[34:35] op_sel_hi:[1,0,1] neg_lo:[0,0,1] neg_hi:[0,0,1]
	v_pk_fma_f32 v[28:29], v[28:29], v[0:1], v[32:33] op_sel_hi:[1,0,1] neg_lo:[0,0,1] neg_hi:[0,0,1]
	v_mul_f32_e32 v48, v30, v30
	v_mul_f32_e32 v40, v28, v28
	v_mul_f32_e32 v42, v29, v29
	v_mul_f32_e32 v56, v31, v31
	v_pk_add_f32 v[32:33], v[40:41], v[42:43]
	v_pk_add_f32 v[34:35], v[48:49], v[56:57]
	v_pk_mul_f32 v[24:25], v[24:25], v[2:3] op_sel_hi:[1,0]
	v_lshlrev_b32_e32 v48, 2, v134
	v_pk_add_f32 v[32:33], v[32:33], v[34:35]
	v_pk_mul_f32 v[34:35], v[26:27], v[2:3] op_sel_hi:[1,0]
	v_pk_fma_f32 v[20:21], v[20:21], v[0:1], v[24:25] op_sel_hi:[1,0,1] neg_lo:[0,0,1] neg_hi:[0,0,1]
	global_load_dwordx4 v[24:27], v48, s[14:15]
	v_pk_mul_f32 v[8:9], v[8:9], v[2:3] op_sel_hi:[1,0]
	v_pk_fma_f32 v[22:23], v[22:23], v[0:1], v[34:35] op_sel_hi:[1,0,1] neg_lo:[0,0,1] neg_hi:[0,0,1]
	v_pk_fma_f32 v[8:9], v[16:17], v[0:1], v[8:9] op_sel_hi:[1,0,1] neg_lo:[0,0,1] neg_hi:[0,0,1]
	v_pk_mul_f32 v[34:35], v[22:23], v[22:23]
	v_pk_mul_f32 v[40:41], v[20:21], v[20:21]
	v_pk_mul_f32 v[10:11], v[10:11], v[2:3] op_sel_hi:[1,0]
	v_mul_f32_e32 v16, v8, v8
	v_pk_mov_b32 v[42:43], v[40:41], v[34:35] op_sel:[1,0]
	v_mov_b32_e32 v41, v35
	v_pk_fma_f32 v[10:11], v[18:19], v[0:1], v[10:11] op_sel_hi:[1,0,1] neg_lo:[0,0,1] neg_hi:[0,0,1]
	v_pk_fma_f32 v[16:17], v[8:9], v[8:9], v[16:17] op_sel_hi:[1,1,0]
	v_pk_add_f32 v[34:35], v[42:43], v[40:41]
	v_mul_f32_e32 v16, v10, v10
	v_pk_mul_f32 v[4:5], v[4:5], v[2:3] op_sel_hi:[1,0]
	v_pk_mul_f32 v[2:3], v[6:7], v[2:3] op_sel_hi:[1,0]
	v_pk_add_f32 v[32:33], v[32:33], v[32:33] op_sel_hi:[0,1]
	v_pk_add_f32 v[34:35], v[34:35], v[34:35] op_sel_hi:[0,1]
	v_pk_fma_f32 v[18:19], v[10:11], v[10:11], v[16:17] op_sel_hi:[1,1,0]
	v_pk_fma_f32 v[6:7], v[14:15], v[0:1], v[2:3] op_sel_hi:[1,0,1] neg_lo:[0,0,1] neg_hi:[0,0,1]
	v_pk_fma_f32 v[12:13], v[12:13], v[0:1], v[4:5] op_sel_hi:[1,0,1] neg_lo:[0,0,1] neg_hi:[0,0,1]
	v_mul_f32_e32 v34, v6, v6
	v_mul_f32_e32 v16, v12, v12
	v_mul_f32_e32 v18, v13, v13
	v_mul_f32_e32 v32, v7, v7
	v_pk_add_f32 v[2:3], v[16:17], v[18:19]
	v_pk_add_f32 v[4:5], v[34:35], v[32:33]
	s_nop 0
	v_pk_add_f32 v[2:3], v[2:3], v[4:5]
	s_nop 0
	v_add_f32_e32 v0, v2, v3
	ds_bpermute_b32 v2, v74, v0
	s_waitcnt lgkmcnt(0)
	v_add_f32_e32 v0, v0, v2
	ds_bpermute_b32 v2, v72, v0
	s_waitcnt lgkmcnt(0)
; __device__ __forceinline__ unsigned pk2(float lo, float hi) { f32x2 v = {lo, hi}; bf16x2_t b = __builtin_convertvector(v, bf16x2_t); return __builtin_bit_cast(unsigned, b); }
; __device__ __forceinline__ void att_final(const AttAcc& A, float l0, float l1, float lam, const float* subg, bf16_t* orow, int g) {
;     ...
;     const float rs = 0.8f / sqrtf(ss * (1.f / 128.f) + EPS);
; #pragma unroll
;     for (int d = 0; d < 8; ++d) { const f32x4 gg = *(const f32x4*)(subg + 16 * d + 4 * g);
;         u32x2 w; w.x = pk2(o[d][0] * rs * gg[0], o[d][1] * rs * gg[1]); w.y = pk2(o[d][2] * rs * gg[2], o[d][3] * rs * gg[3]);
;         *(u32x2*)(orow + 16 * d + 4 * g) = w; }
	v_add_f32_e32 v0, v0, v2
	v_fmamk_f32 v0, v0, 0x3c000000, v166
	v_mul_f32_e32 v2, 0x4f800000, v0
	v_cmp_gt_f32_e32 vcc, s35, v0
	s_nop 1
	v_cndmask_b32_e32 v0, v0, v2, vcc
	v_sqrt_f32_e32 v2, v0
	s_nop 0
	v_add_u32_e32 v3, -1, v2
	v_fma_f32 v4, -v3, v2, v0
	v_cmp_ge_f32_e64 s[2:3], 0, v4
	v_add_u32_e32 v4, 1, v2
	s_nop 0
	v_cndmask_b32_e64 v3, v2, v3, s[2:3]
	v_fma_f32 v2, -v4, v2, v0
	v_cmp_lt_f32_e64 s[2:3], 0, v2
	s_nop 1
	v_cndmask_b32_e64 v2, v3, v4, s[2:3]
	v_mul_f32_e32 v3, 0x37800000, v2
	v_cndmask_b32_e32 v2, v2, v3, vcc
	v_cmp_class_f32_e32 vcc, v0, v167
	s_nop 1
	v_cndmask_b32_e32 v0, v2, v0, vcc
	v_div_scale_f32 v2, s[2:3], v0, v0, s42
	v_rcp_f32_e32 v3, v2
	s_mov_b64 s[2:3], 0
	v_fma_f32 v4, -v2, v3, 1.0
	v_fmac_f32_e32 v3, v4, v3
	v_div_scale_f32 v4, vcc, s42, v0, s42
	v_mul_f32_e32 v5, v4, v3
	v_fma_f32 v14, -v2, v5, v4
	v_fmac_f32_e32 v5, v14, v3
	v_fma_f32 v2, -v2, v5, v4
	v_div_fmas_f32 v2, v2, v3, v5
	v_div_fixup_f32 v14, v2, v0, s42
	v_pk_mul_f32 v[2:3], v[60:61], v[14:15] op_sel_hi:[1,0]
	v_pk_mul_f32 v[4:5], v[62:63], v[14:15] op_sel_hi:[1,0]
	v_lshlrev_b32_e32 v0, 1, v134
	s_waitcnt vmcnt(0)
	v_pk_mul_f32 v[2:3], v[24:25], v[2:3]
	v_pk_mul_f32 v[4:5], v[26:27], v[4:5]
	v_lshl_add_u64 v[16:17], v[150:151], 0, v[0:1]
	v_cvt_pk_bf16_f32 v2, v2, v3
	v_cvt_pk_bf16_f32 v3, v4, v5
	global_store_dwordx2 v[16:17], v[2:3], off sc1
	global_load_dwordx4 v[2:5], v48, s[14:15] offset:64
	v_pk_mul_f32 v[18:19], v[52:53], v[14:15] op_sel_hi:[1,0]
	v_pk_mul_f32 v[24:25], v[54:55], v[14:15] op_sel_hi:[1,0]
	v_pk_mul_f32 v[8:9], v[8:9], v[14:15] op_sel_hi:[1,0]
	v_pk_mul_f32 v[10:11], v[10:11], v[14:15] op_sel_hi:[1,0]
	v_pk_mul_f32 v[6:7], v[6:7], v[14:15] op_sel_hi:[1,0]
	s_waitcnt vmcnt(0)
	v_pk_mul_f32 v[2:3], v[2:3], v[18:19]
	v_pk_mul_f32 v[4:5], v[4:5], v[24:25]
	v_cvt_pk_bf16_f32 v2, v2, v3
	v_cvt_pk_bf16_f32 v3, v4, v5
	global_store_dwordx2 v[16:17], v[2:3], off offset:32 sc1
	global_load_dwordx4 v[2:5], v48, s[14:15] offset:128
	v_pk_mul_f32 v[18:19], v[44:45], v[14:15] op_sel_hi:[1,0]
	v_pk_mul_f32 v[24:25], v[46:47], v[14:15] op_sel_hi:[1,0]
	s_waitcnt vmcnt(0)
	v_pk_mul_f32 v[2:3], v[2:3], v[18:19]
	v_pk_mul_f32 v[4:5], v[4:5], v[24:25]
	v_cvt_pk_bf16_f32 v2, v2, v3
	v_cvt_pk_bf16_f32 v3, v4, v5
	global_store_dwordx2 v[16:17], v[2:3], off offset:64 sc1
	global_load_dwordx4 v[2:5], v48, s[14:15] offset:192
	v_pk_mul_f32 v[18:19], v[36:37], v[14:15] op_sel_hi:[1,0]
	v_pk_mul_f32 v[24:25], v[38:39], v[14:15] op_sel_hi:[1,0]
	s_waitcnt vmcnt(0)
	v_pk_mul_f32 v[2:3], v[2:3], v[18:19]
	v_pk_mul_f32 v[4:5], v[4:5], v[24:25]
	v_cvt_pk_bf16_f32 v2, v2, v3
	v_cvt_pk_bf16_f32 v3, v4, v5
	global_store_dwordx2 v[16:17], v[2:3], off offset:96 sc1
	global_load_dwordx4 v[2:5], v48, s[14:15] offset:256
	v_pk_mul_f32 v[18:19], v[28:29], v[14:15] op_sel_hi:[1,0]
	v_pk_mul_f32 v[24:25], v[30:31], v[14:15] op_sel_hi:[1,0]
	s_waitcnt vmcnt(0)
	v_pk_mul_f32 v[2:3], v[2:3], v[18:19]
	v_pk_mul_f32 v[4:5], v[4:5], v[24:25]
	v_cvt_pk_bf16_f32 v2, v2, v3
	v_cvt_pk_bf16_f32 v3, v4, v5
	global_store_dwordx2 v[16:17], v[2:3], off offset:128 sc1
	global_load_dwordx4 v[2:5], v48, s[14:15] offset:320
	v_pk_mul_f32 v[18:19], v[20:21], v[14:15] op_sel_hi:[1,0]
	v_pk_mul_f32 v[20:21], v[22:23], v[14:15] op_sel_hi:[1,0]
	s_waitcnt vmcnt(0)
	v_pk_mul_f32 v[2:3], v[2:3], v[18:19]
	v_pk_mul_f32 v[4:5], v[4:5], v[20:21]
	v_cvt_pk_bf16_f32 v2, v2, v3
	v_cvt_pk_bf16_f32 v3, v4, v5
	global_store_dwordx2 v[16:17], v[2:3], off offset:160 sc1
	global_load_dwordx4 v[2:5], v48, s[14:15] offset:384
	s_waitcnt vmcnt(0)
	v_pk_mul_f32 v[2:3], v[2:3], v[8:9]
	v_pk_mul_f32 v[4:5], v[4:5], v[10:11]
	v_cvt_pk_bf16_f32 v2, v2, v3
	v_cvt_pk_bf16_f32 v3, v4, v5
	global_store_dwordx2 v[16:17], v[2:3], off offset:192 sc1
	global_load_dwordx4 v[2:5], v48, s[14:15] offset:448
	v_pk_mul_f32 v[8:9], v[12:13], v[14:15] op_sel_hi:[1,0]
	s_waitcnt vmcnt(0)
	v_pk_mul_f32 v[4:5], v[4:5], v[6:7]
	v_pk_mul_f32 v[2:3], v[2:3], v[8:9]
	s_nop 0
	v_cvt_pk_bf16_f32 v2, v2, v3
	v_cvt_pk_bf16_f32 v3, v4, v5
	global_store_dwordx2 v[16:17], v[2:3], off offset:224 sc1

;     __device__ __forceinline__ const float* in(int i) const { return (const float*)ptr(i); }
;     __device__ __forceinline__ unsigned char* ws() const { return (unsigned char*)ptr(37); }
; #define ws (p.ws())
; __device__ __forceinline__ void phase_lnpass(const Ctx& p) {
;     const int tid = threadIdx.x, c8 = tid & 7, h = (tid >> 3) & 7, rr = tid >> 6, c = h * 64 + 8 * c8;
;     const bf16_t* ZRW = (const bf16_t*)(p.ws() + WS_ZRW); const bf16_t* AB = (const bf16_t*)(p.ws() + WS_ABUF); const bf16_t* GG = (const bf16_t*)(p.ws() + WS_GG);
;     bf16_t* ORW = (bf16_t*)(p.ws() + WS_ORW);
;     float mur[8], muk[8], muv[8], kac[8], rkc[8], lg[8], lb[8];
; #pragma unroll
;     for (int e = 0; e < 8; ++e) { mur[e] = p.in(17)[c + e]; muk[e] = p.in(17)[512 + c + e]; muv[e] = p.in(17)[1024 + c + e]; kac[e] = p.in(24)[c + e]; rkc[e] = p.in(25)[c + e]; lg[e] = p.in(26)[c + e]; lb[e] = p.in(27)[c + e]; }
;     struct LR { u32x4 zr, zrp, zk, zkp, zv, zvp, ab, gg, yy; };
;     auto ldrow = [&](LR& L, int row) {
;         const int rp = row > 0 ? row - 1 : 0;
;         L.zr = *(const u32x4*)(ZRW + (size_t)row * SHW + c); L.zrp = *(const u32x4*)(ZRW + (size_t)rp * SHW + c);
;         L.zk = *(const u32x4*)(ZRW + (size_t)row * SHW + 512 + c); L.zkp = *(const u32x4*)(ZRW + (size_t)rp * SHW + 512 + c);
;         L.zv = *(const u32x4*)(ZRW + (size_t)row * SHW + 1024 + c); L.zvp = *(const u32x4*)(ZRW + (size_t)rp * SHW + 1024 + c);
;         L.ab = *(const u32x4*)(AB + (size_t)row * 512 + c); L.gg = *(const u32x4*)(GG + (size_t)row * 512 + c); L.yy = *(const u32x4*)(ORW + (size_t)row * 512 + c);
;     };
;     LR La, Lb;
;     if ((int)blockIdx.x < MR / 8) ldrow(La, blockIdx.x * 8 + rr);
;     for (int it = blockIdx.x; it < MR / 8; it += gridDim.x) {
;         const int row = it * 8 + rr;
;         const bool more = it + (int)gridDim.x < MR / 8;
;         if (more) ldrow(Lb, (it + gridDim.x) * 8 + rr);
.Lln_w1_x:
	s_or_b64 exec, exec, s[2:3]
	s_waitcnt lgkmcnt(0)
	s_barrier
	s_sub_u32 s70, s28, 4
	s_movk_i32 s72, 0x7c
	s_add_i32 s2, 0, 0x23528
	s_waitcnt vmcnt(0)
	v_mov_b32_e32 v0, s2
	ds_read_b64 v[0:1], v0
	s_add_i32 s2, 0, 0x23488
	v_mov_b32_e32 v2, s2
	s_add_i32 s6, 0, 0x234c0
	ds_read_b64 v[8:9], v2
	s_waitcnt lgkmcnt(0)
	v_readfirstlane_b32 s2, v0
	v_mov_b32_e32 v0, s6
	s_add_i32 s6, 0, 0x234d0
	v_mov_b32_e32 v4, s6
	v_readfirstlane_b32 s3, v1
	ds_read_b128 v[0:3], v0
	ds_read_b128 v[4:7], v4
	v_readfirstlane_b32 s12, v8
	v_readfirstlane_b32 s13, v9
	s_cmpk_gt_i32 s70, 0x513
	s_waitcnt lgkmcnt(1)
	v_readfirstlane_b32 s14, v0
	v_readfirstlane_b32 s15, v1
	v_readfirstlane_b32 s16, v2
	v_readfirstlane_b32 s17, v3
	s_waitcnt lgkmcnt(0)
	v_readfirstlane_b32 s10, v4
	v_readfirstlane_b32 s11, v5
	v_readfirstlane_b32 s8, v6
	v_readfirstlane_b32 s9, v7
	s_cbranch_scc1 .Lln1_done
	v_lshlrev_b32_e32 v0, 3, v180
	v_and_b32_e32 v56, 0x1f8, v0
	v_mov_b32_e32 v141, 0
	v_lshlrev_b32_e32 v140, 2, v56
	v_lshl_add_u64 v[32:33], s[12:13], 0, v[140:141]
	global_load_dwordx4 v[0:3], v140, s[12:13] offset:16
	global_load_dwordx4 v[4:7], v140, s[12:13]
	global_load_dwordx4 v[8:11], v140, s[12:13] offset:2064
	global_load_dwordx4 v[12:15], v140, s[12:13] offset:2048
	global_load_dwordx4 v[16:19], v140, s[14:15] offset:16
	global_load_dwordx4 v[20:23], v140, s[14:15]
	global_load_dwordx4 v[24:27], v140, s[16:17] offset:16
	global_load_dwordx4 v[28:31], v140, s[16:17]
	s_movk_i32 s12, 0x1000
	v_add_co_u32_e32 v60, vcc, s12, v32
	s_mov_b64 s[6:7], 0x1000
	s_nop 0
	v_addc_co_u32_e32 v61, vcc, 0, v33, vcc
	v_lshl_add_u64 v[58:59], v[32:33], 0, s[6:7]
	global_load_dwordx4 v[32:35], v[60:61], off
	global_load_dwordx4 v[36:39], v[58:59], off offset:16
	global_load_dwordx4 v[40:43], v140, s[10:11] offset:16
	global_load_dwordx4 v[44:47], v140, s[10:11]
	global_load_dwordx4 v[48:51], v140, s[8:9] offset:16
	global_load_dwordx4 v[52:55], v140, s[8:9]
	s_add_u32 s8, s2, 0x8340000
	s_addc_u32 s9, s3, 0
	s_add_u32 s10, s2, 0x4240000
	s_addc_u32 s11, s3, 0
	s_add_u32 s14, s2, 0x3200000
	v_lshrrev_b32_e32 v152, 6, v180
	s_addc_u32 s15, s3, 0
	s_lshl_b32 s12, s70, 3
	v_add_u32_e32 v58, s12, v152
	v_max_i32_e32 v57, 1, v58
	s_movk_i32 s13, 0xe00
	v_mov_b64_e32 v[60:61], s[8:9]
	v_add_u32_e32 v57, -1, v57
	v_mad_i64_i32 v[62:63], s[16:17], v58, s13, v[60:61]
	v_lshlrev_b32_e32 v140, 1, v56
	v_lshl_add_u64 v[62:63], v[62:63], 0, v[140:141]
	v_mad_u64_u32 v[60:61], s[16:17], v57, s13, v[60:61]
	v_ashrrev_i32_e32 v59, 31, v58
	v_lshl_add_u64 v[60:61], v[60:61], 0, v[140:141]
	global_load_dwordx4 v[104:107], v[62:63], off
	global_load_dwordx4 v[108:111], v[62:63], off offset:1024
	global_load_dwordx4 v[124:127], v[60:61], off
	global_load_dwordx4 v[92:95], v[62:63], off offset:2048
	global_load_dwordx4 v[116:119], v[60:61], off offset:1024
	global_load_dwordx4 v[120:123], v[60:61], off offset:2048
	v_lshlrev_b64 v[58:59], 10, v[58:59]
	v_lshl_add_u64 v[60:61], s[14:15], 0, v[58:59]
	v_lshl_add_u64 v[62:63], s[10:11], 0, v[58:59]
	v_lshl_add_u64 v[58:59], s[2:3], 0, v[58:59]
	v_lshl_add_u64 v[60:61], v[60:61], 0, v[140:141]
	v_lshl_add_u64 v[58:59], v[58:59], 0, v[140:141]
	v_lshl_add_u64 v[62:63], v[62:63], 0, v[140:141]
	global_load_dwordx4 v[112:115], v[60:61], off
	global_load_dwordx4 v[100:103], v[62:63], off
	global_load_dwordx4 v[96:99], v[58:59], off
	v_lshl_add_u64 v[146:147], s[2:3], 0, v[140:141]
	s_add_i32 s2, s70, s72
	v_lshl_add_u64 v[142:143], s[14:15], 0, v[140:141]
	v_lshl_add_u64 v[144:145], s[10:11], 0, v[140:141]
	v_lshl_add_u64 v[148:149], s[8:9], 0, v[140:141]
	s_lshl_b32 s14, s2, 3
	s_lshl_b32 s15, s72, 3
	s_movk_i32 s16, 0x4000
	s_movk_i32 s17, 0x3fff
	s_add_i32 s18, 0, 0x23428
	s_movk_i32 s19, 0x1c00
	v_lshlrev_b32_e32 v140, 2, v56
	v_mov_b32_e32 v153, 0x3a27c5ac
	s_mov_b32 s20, 0xf800000
	v_mov_b32_e32 v154, 0x260
	v_mov_b32_e32 v155, 0xfff
	s_mov_b32 s21, s70
	s_branch .Lln1_c

; __device__ __forceinline__ void phase_lnpass(const Ctx& p) {
;     ...
;     auto ldrow = [&](LR& L, int row) {
;         const int rp = row > 0 ? row - 1 : 0;
;         L.zr = *(const u32x4*)(ZRW + (size_t)row * SHW + c); L.zrp = *(const u32x4*)(ZRW + (size_t)rp * SHW + c);
;         L.zk = *(const u32x4*)(ZRW + (size_t)row * SHW + 512 + c); L.zkp = *(const u32x4*)(ZRW + (size_t)rp * SHW + 512 + c);
;         L.zv = *(const u32x4*)(ZRW + (size_t)row * SHW + 1024 + c); L.zvp = *(const u32x4*)(ZRW + (size_t)rp * SHW + 1024 + c);
;         L.ab = *(const u32x4*)(AB + (size_t)row * 512 + c); L.gg = *(const u32x4*)(GG + (size_t)row * 512 + c); L.yy = *(const u32x4*)(ORW + (size_t)row * 512 + c);
;     };
;     LR La, Lb;
;     if ((int)blockIdx.x < MR / 8) ldrow(La, blockIdx.x * 8 + rr);
;     for (int it = blockIdx.x; it < MR / 8; it += gridDim.x) {
;         const int row = it * 8 + rr;
;         const bool more = it + (int)gridDim.x < MR / 8;
;         if (more) ldrow(Lb, (it + gridDim.x) * 8 + rr);
.Lln1_c:
	s_add_i32 s21, s21, s72
	s_cmpk_gt_i32 s21, 0x513
	s_cselect_b64 s[8:9], -1, 0
	s_and_b64 vcc, exec, s[8:9]
	s_cbranch_vccnz .Lln1_d
	v_add_u32_e32 v80, s14, v152
	v_max_i32_e32 v56, 1, v80
	v_add_u32_e32 v56, -1, v56
	v_mad_i64_i32 v[68:69], s[2:3], v80, s13, v[148:149]
	v_mad_u64_u32 v[76:77], s[2:3], v56, s13, v[148:149]
	global_load_dwordx4 v[56:59], v[68:69], off
	global_load_dwordx4 v[64:67], v[68:69], off offset:1024
	global_load_dwordx4 v[60:63], v[76:77], off
	global_load_dwordx4 v[72:75], v[68:69], off offset:2048
	s_nop 0
	global_load_dwordx4 v[68:71], v[76:77], off offset:1024
	s_nop 0
	global_load_dwordx4 v[76:79], v[76:77], off offset:2048
	v_ashrrev_i32_e32 v81, 31, v80
	v_lshlrev_b64 v[88:89], 10, v[80:81]
	v_lshl_add_u64 v[80:81], v[142:143], 0, v[88:89]
	v_lshl_add_u64 v[84:85], v[144:145], 0, v[88:89]
	v_lshl_add_u64 v[88:89], v[146:147], 0, v[88:89]
	global_load_dwordx4 v[80:83], v[80:81], off
	s_nop 0
	global_load_dwordx4 v[84:87], v[84:85], off
	s_nop 0
	global_load_dwordx4 v[88:91], v[88:89], off

;     __device__ __forceinline__ unsigned char* ws() const { return (unsigned char*)ptr(37); }
; #define ws (p.ws())
; __device__ __forceinline__ void sub_barrier(const Ctx& p, unsigned n) {
;     asm volatile("s_waitcnt vmcnt(0)" ::: "memory");
;     __syncthreads();
;     if (threadIdx.x == 0) {
;         unsigned* c = (unsigned*)(p.ws() + WS_CTR) + 128;
;         __builtin_amdgcn_fence(__ATOMIC_RELEASE, "agent");
;         asm volatile("s_waitcnt vmcnt(0)" ::: "memory");
;         __hip_atomic_fetch_add(c, 1u, __ATOMIC_RELAXED, __HIP_MEMORY_SCOPE_AGENT);
;         while (__hip_atomic_load(c, __ATOMIC_RELAXED, __HIP_MEMORY_SCOPE_AGENT) < n) __builtin_amdgcn_s_sleep(20);
.Lln1_done:
.LBB0_1819:
	s_cmpk_lt_u32 s28, 0x80
	s_cbranch_scc1 .LBB0_1869
	s_waitcnt vmcnt(0)
	v_readlane_b32 s0, v238, 0
	v_readlane_b32 s1, v238, 1
	s_waitcnt vmcnt(0) lgkmcnt(0)
	s_barrier
	s_and_saveexec_b64 s[2:3], s[0:1]
	s_cbranch_execz .LBB0_1827
	s_add_i32 s4, 0, 0x23528
	v_mov_b32_e32 v0, s4
	ds_read_b64 v[0:1], v0
	s_mov_b64 s[6:7], exec
	s_waitcnt lgkmcnt(0)
	s_waitcnt vmcnt(0)
	v_readfirstlane_b32 s4, v0
	v_mbcnt_lo_u32_b32 v0, s6, 0
	v_readfirstlane_b32 s5, v1
	s_add_u32 s4, s4, 0x3180200
	v_mbcnt_hi_u32_b32 v0, s7, v0
	s_addc_u32 s5, s5, 0
	v_cmp_eq_u32_e32 vcc, 0, v0
	s_and_saveexec_b64 s[8:9], vcc
	s_cbranch_execz .LBB0_1823
	s_bcnt1_i32_b64 s6, s[6:7]
	v_mov_b32_e32 v0, 0
	v_mov_b32_e32 v1, s6
	global_atomic_add v0, v1, s[4:5]

;     __device__ __forceinline__ const float* in(int i) const { return (const float*)ptr(i); }
;     __device__ __forceinline__ unsigned char* ws() const { return (unsigned char*)ptr(37); }
; #define ws (p.ws())
; __device__ __forceinline__ void phase_lnpass(const Ctx& p) {
;     const int tid = threadIdx.x, c8 = tid & 7, h = (tid >> 3) & 7, rr = tid >> 6, c = h * 64 + 8 * c8;
;     const bf16_t* ZRW = (const bf16_t*)(p.ws() + WS_ZRW); const bf16_t* AB = (const bf16_t*)(p.ws() + WS_ABUF); const bf16_t* GG = (const bf16_t*)(p.ws() + WS_GG);
;     bf16_t* ORW = (bf16_t*)(p.ws() + WS_ORW);
;     float mur[8], muk[8], muv[8], kac[8], rkc[8], lg[8], lb[8];
; #pragma unroll
;     for (int e = 0; e < 8; ++e) { mur[e] = p.in(17)[c + e]; muk[e] = p.in(17)[512 + c + e]; muv[e] = p.in(17)[1024 + c + e]; kac[e] = p.in(24)[c + e]; rkc[e] = p.in(25)[c + e]; lg[e] = p.in(26)[c + e]; lb[e] = p.in(27)[c + e]; }
;     struct LR { u32x4 zr, zrp, zk, zkp, zv, zvp, ab, gg, yy; };
;     auto ldrow = [&](LR& L, int row) {
;         const int rp = row > 0 ? row - 1 : 0;
;         L.zr = *(const u32x4*)(ZRW + (size_t)row * SHW + c); L.zrp = *(const u32x4*)(ZRW + (size_t)rp * SHW + c);
;         L.zk = *(const u32x4*)(ZRW + (size_t)row * SHW + 512 + c); L.zkp = *(const u32x4*)(ZRW + (size_t)rp * SHW + 512 + c);
;         L.zv = *(const u32x4*)(ZRW + (size_t)row * SHW + 1024 + c); L.zvp = *(const u32x4*)(ZRW + (size_t)rp * SHW + 1024 + c);
;         L.ab = *(const u32x4*)(AB + (size_t)row * 512 + c); L.gg = *(const u32x4*)(GG + (size_t)row * 512 + c); L.yy = *(const u32x4*)(ORW + (size_t)row * 512 + c);
;     };
;     LR La, Lb;
;     if ((int)blockIdx.x < MR / 8) ldrow(La, blockIdx.x * 8 + rr);
;     for (int it = blockIdx.x; it < MR / 8; it += gridDim.x) {
;         const int row = it * 8 + rr;
;         const bool more = it + (int)gridDim.x < MR / 8;
;         if (more) ldrow(Lb, (it + gridDim.x) * 8 + rr);
.Lln_w2_x:
	s_or_b64 exec, exec, s[2:3]
	s_waitcnt lgkmcnt(0)
	s_barrier
	s_movk_i32 s72, 0x80
	s_add_i32 s71, s28, 0x494
	s_add_i32 s2, 0, 0x23528
	s_waitcnt vmcnt(0)
	v_mov_b32_e32 v0, s2
	ds_read_b64 v[0:1], v0
	s_add_i32 s2, 0, 0x23488
	v_mov_b32_e32 v2, s2
	s_add_i32 s6, 0, 0x234c0
	ds_read_b64 v[8:9], v2
	s_waitcnt lgkmcnt(0)
	v_readfirstlane_b32 s2, v0
	v_mov_b32_e32 v0, s6
	s_add_i32 s6, 0, 0x234d0
	v_mov_b32_e32 v4, s6
	v_readfirstlane_b32 s3, v1
	ds_read_b128 v[0:3], v0
	ds_read_b128 v[4:7], v4
	v_readfirstlane_b32 s12, v8
	v_readfirstlane_b32 s13, v9
	s_cmpk_gt_i32 s71, 0x80f
	s_waitcnt lgkmcnt(1)
	v_readfirstlane_b32 s14, v0
	v_readfirstlane_b32 s15, v1
	v_readfirstlane_b32 s16, v2
	v_readfirstlane_b32 s17, v3
	s_waitcnt lgkmcnt(0)
	v_readfirstlane_b32 s10, v4
	v_readfirstlane_b32 s11, v5
	v_readfirstlane_b32 s8, v6
	v_readfirstlane_b32 s9, v7
	s_cbranch_scc1 .Lln2_done
	v_lshlrev_b32_e32 v0, 3, v180
	v_and_b32_e32 v56, 0x1f8, v0
	v_mov_b32_e32 v141, 0
	v_lshlrev_b32_e32 v140, 2, v56
	v_lshl_add_u64 v[32:33], s[12:13], 0, v[140:141]
	global_load_dwordx4 v[0:3], v140, s[12:13] offset:16
	global_load_dwordx4 v[4:7], v140, s[12:13]
	global_load_dwordx4 v[8:11], v140, s[12:13] offset:2064
	global_load_dwordx4 v[12:15], v140, s[12:13] offset:2048
	global_load_dwordx4 v[16:19], v140, s[14:15] offset:16
	global_load_dwordx4 v[20:23], v140, s[14:15]
	global_load_dwordx4 v[24:27], v140, s[16:17] offset:16
	global_load_dwordx4 v[28:31], v140, s[16:17]
	s_movk_i32 s12, 0x1000
	v_add_co_u32_e32 v60, vcc, s12, v32
	s_mov_b64 s[6:7], 0x1000
	s_nop 0
	v_addc_co_u32_e32 v61, vcc, 0, v33, vcc
	v_lshl_add_u64 v[58:59], v[32:33], 0, s[6:7]
	global_load_dwordx4 v[32:35], v[60:61], off
	global_load_dwordx4 v[36:39], v[58:59], off offset:16
	global_load_dwordx4 v[40:43], v140, s[10:11] offset:16
	global_load_dwordx4 v[44:47], v140, s[10:11]
	global_load_dwordx4 v[48:51], v140, s[8:9] offset:16
	global_load_dwordx4 v[52:55], v140, s[8:9]
	s_add_u32 s8, s2, 0x8340000
	s_addc_u32 s9, s3, 0
	s_add_u32 s10, s2, 0x4240000
	s_addc_u32 s11, s3, 0
	s_add_u32 s14, s2, 0x3200000
	v_lshrrev_b32_e32 v152, 6, v180
	s_addc_u32 s15, s3, 0
	s_lshl_b32 s12, s71, 3
	v_add_u32_e32 v58, s12, v152
	v_max_i32_e32 v57, 1, v58
	s_movk_i32 s13, 0xe00
	v_mov_b64_e32 v[60:61], s[8:9]
	v_add_u32_e32 v57, -1, v57
	v_mad_i64_i32 v[62:63], s[16:17], v58, s13, v[60:61]
	v_lshlrev_b32_e32 v140, 1, v56
	v_lshl_add_u64 v[62:63], v[62:63], 0, v[140:141]
	v_mad_u64_u32 v[60:61], s[16:17], v57, s13, v[60:61]
	v_ashrrev_i32_e32 v59, 31, v58
	v_lshl_add_u64 v[60:61], v[60:61], 0, v[140:141]
	global_load_dwordx4 v[104:107], v[62:63], off
	global_load_dwordx4 v[108:111], v[62:63], off offset:1024
	global_load_dwordx4 v[124:127], v[60:61], off
	global_load_dwordx4 v[92:95], v[62:63], off offset:2048
	global_load_dwordx4 v[116:119], v[60:61], off offset:1024
	global_load_dwordx4 v[120:123], v[60:61], off offset:2048
	v_lshlrev_b64 v[58:59], 10, v[58:59]
	v_lshl_add_u64 v[60:61], s[14:15], 0, v[58:59]
	v_lshl_add_u64 v[62:63], s[10:11], 0, v[58:59]
	v_lshl_add_u64 v[58:59], s[2:3], 0, v[58:59]
	v_lshl_add_u64 v[60:61], v[60:61], 0, v[140:141]
	v_lshl_add_u64 v[58:59], v[58:59], 0, v[140:141]
	v_lshl_add_u64 v[62:63], v[62:63], 0, v[140:141]
	global_load_dwordx4 v[112:115], v[60:61], off
	global_load_dwordx4 v[100:103], v[62:63], off
	global_load_dwordx4 v[96:99], v[58:59], off
	v_lshl_add_u64 v[146:147], s[2:3], 0, v[140:141]
	s_add_i32 s2, s71, s72
	v_lshl_add_u64 v[142:143], s[14:15], 0, v[140:141]
	v_lshl_add_u64 v[144:145], s[10:11], 0, v[140:141]
	v_lshl_add_u64 v[148:149], s[8:9], 0, v[140:141]
	s_lshl_b32 s14, s2, 3
	s_lshl_b32 s15, s72, 3
	s_movk_i32 s16, 0x4000
	s_movk_i32 s17, 0x3fff
	s_add_i32 s18, 0, 0x23428
	s_movk_i32 s19, 0x1c00
	v_lshlrev_b32_e32 v140, 2, v56
	v_mov_b32_e32 v153, 0x3a27c5ac
	s_mov_b32 s20, 0xf800000
	v_mov_b32_e32 v154, 0x260
	v_mov_b32_e32 v155, 0xfff
	s_mov_b32 s21, s71
	s_branch .Lln2_c
